# phase-2 weight conversions stored write-through (sc1) and counted; no L2 write-back by the last arriver of seam 3
# speedup vs baseline: 1.0362x; 1.0025x over previous
; #define LAS __attribute__((address_space(3)))
; __device__ __forceinline__ unsigned pk2(float lo, float hi) { return pg8::cvt_pk_bf16(lo, hi); }
; template <int MAP>
; __device__ __forceinline__ void transpose_item(const float* W, int K, int N, bf16_t* WT, const float* gk, LAS float* scr, int item, int nblk, int lane) {
;     ...
;     for (int i = 0; i < 32; ++i) scr[(2 * i + (lane >> 5)) * 33 + (lane & 31)] = tv[i];
;     asm volatile("s_waitcnt lgkmcnt(0)" ::: "memory");
;     const int c = lane & 7;
; #pragma unroll
;     for (int j = 0; j < 4; ++j) { const int n = (lane >> 3) + 8 * j; const LAS float* s = scr + (8 * c) * 33 + n;
;         u32x4 o; o.x = pk2(s[0 * 33], s[1 * 33]); o.y = pk2(s[2 * 33], s[3 * 33]); o.z = pk2(s[4 * 33], s[5 * 33]); o.w = pk2(s[6 * 33], s[7 * 33]);
;         *(u32x4*)(WT + (size_t)(n0 + n) * K + k0 + 8 * c) = o; }
;     asm volatile("s_waitcnt lgkmcnt(0)" ::: "memory");
.LBB0_478:
	s_waitcnt vmcnt(0)
	ds_write2_b32 v49, v10, v11 offset1:66
	ds_write2_b32 v49, v12, v13 offset0:132 offset1:198
	ds_write2_b32 v57, v14, v15 offset0:8 offset1:74
	ds_write2_b32 v57, v16, v17 offset0:140 offset1:206
	ds_write2_b32 v58, v18, v19 offset0:16 offset1:82
	ds_write2_b32 v58, v20, v21 offset0:148 offset1:214
	ds_write2_b32 v59, v22, v23 offset0:24 offset1:90
	ds_write2_b32 v59, v26, v27 offset0:156 offset1:222
	ds_write2_b32 v60, v30, v31 offset0:32 offset1:98
	ds_write2_b32 v60, v32, v33 offset0:164 offset1:230
	ds_write2_b32 v61, v34, v35 offset0:40 offset1:106
	ds_write2_b32 v61, v36, v37 offset0:172 offset1:238
	ds_write2_b32 v62, v38, v39 offset0:48 offset1:114
	ds_write2_b32 v62, v40, v41 offset0:180 offset1:246
	ds_write2_b32 v63, v42, v43 offset0:56 offset1:122
	ds_write2_b32 v63, v44, v45 offset0:188 offset1:254
	s_waitcnt lgkmcnt(0)
	ds_read2_b32 v[10:11], v51 offset1:33
	s_waitcnt lgkmcnt(0)
	v_cvt_pk_bf16_f32 v10, v10, v11
	ds_read2_b32 v[12:13], v51 offset0:66 offset1:99
	s_waitcnt lgkmcnt(0)
	v_cvt_pk_bf16_f32 v11, v12, v13
	ds_read2_b32 v[12:13], v51 offset0:132 offset1:165
	s_waitcnt lgkmcnt(0)
	v_cvt_pk_bf16_f32 v12, v12, v13
	ds_read2_b32 v[14:15], v51 offset0:198 offset1:231
	v_sub_u32_e32 v0, 0, v9
	s_waitcnt lgkmcnt(0)
	v_cvt_pk_bf16_f32 v13, v14, v15
	v_add3_u32 v14, v50, v55, v0
	v_ashrrev_i32_e32 v9, 31, v8
	v_ashrrev_i32_e32 v15, 31, v14
	v_lshl_add_u64 v[16:17], v[8:9], 1, v[6:7]
	v_lshlrev_b64 v[18:19], 11, v[14:15]
	v_lshl_add_u64 v[18:19], v[16:17], 0, v[18:19]
	global_store_dwordx4 v[18:19], v[10:13], off sc1
	v_add_u32_e32 v18, 8, v14
	ds_read2_b32 v[8:9], v51 offset0:8 offset1:41
	v_ashrrev_i32_e32 v19, 31, v18
	s_waitcnt lgkmcnt(0)
	v_cvt_pk_bf16_f32 v8, v8, v9
	ds_read2_b32 v[10:11], v51 offset0:74 offset1:107
	v_lshlrev_b64 v[18:19], 11, v[18:19]
	s_waitcnt lgkmcnt(0)
	v_cvt_pk_bf16_f32 v9, v10, v11
	ds_read2_b32 v[10:11], v51 offset0:140 offset1:173
	v_lshl_add_u64 v[18:19], v[16:17], 0, v[18:19]
	s_waitcnt lgkmcnt(0)
	v_cvt_pk_bf16_f32 v10, v10, v11
	ds_read2_b32 v[12:13], v51 offset0:206 offset1:239
	s_waitcnt lgkmcnt(0)
	v_cvt_pk_bf16_f32 v11, v12, v13
	global_store_dwordx4 v[18:19], v[8:11], off sc1
	v_add_u32_e32 v18, 16, v14
	ds_read2_b32 v[12:13], v51 offset0:16 offset1:49
	s_waitcnt lgkmcnt(0)
	v_cvt_pk_bf16_f32 v8, v12, v13
	ds_read2_b32 v[10:11], v51 offset0:82 offset1:115
	v_ashrrev_i32_e32 v19, 31, v18
	s_waitcnt lgkmcnt(0)
	v_cvt_pk_bf16_f32 v9, v10, v11
	ds_read2_b32 v[10:11], v51 offset0:148 offset1:181
	v_lshlrev_b64 v[18:19], 11, v[18:19]
	s_waitcnt lgkmcnt(0)
	v_cvt_pk_bf16_f32 v10, v10, v11
	ds_read2_b32 v[12:13], v51 offset0:214 offset1:247
	s_waitcnt lgkmcnt(0)
	v_cvt_pk_bf16_f32 v11, v12, v13
	v_lshl_add_u64 v[18:19], v[16:17], 0, v[18:19]
	ds_read2_b32 v[12:13], v51 offset0:24 offset1:57
	global_store_dwordx4 v[18:19], v[8:11], off sc1
	v_add_u32_e32 v14, 24, v14
	v_ashrrev_i32_e32 v15, 31, v14
	s_waitcnt lgkmcnt(0)
	v_cvt_pk_bf16_f32 v8, v12, v13
	ds_read2_b32 v[10:11], v51 offset0:90 offset1:123
	s_waitcnt lgkmcnt(0)
	v_cvt_pk_bf16_f32 v9, v10, v11
	ds_read2_b32 v[10:11], v51 offset0:156 offset1:189
	s_waitcnt lgkmcnt(0)
	v_cvt_pk_bf16_f32 v10, v10, v11
	ds_read2_b32 v[12:13], v51 offset0:222 offset1:255
	v_lshlrev_b64 v[14:15], 11, v[14:15]
	s_waitcnt lgkmcnt(0)
	v_cvt_pk_bf16_f32 v11, v12, v13
	v_lshl_add_u64 v[12:13], v[16:17], 0, v[14:15]
	global_store_dwordx4 v[12:13], v[8:11], off sc1
	s_waitcnt lgkmcnt(0)

; #define LAS __attribute__((address_space(3)))
; template <int MAP>
; __device__ __forceinline__ void transpose_item(const float* W, int K, int N, bf16_t* WT, const float* gk, LAS float* scr, int item, int nblk, int lane) {
;     const int kb = item / nblk, nb = item % nblk, k0 = 64 * kb, n0 = 32 * nb;
;     const int src = MAP ? win_src_col(n0 + (lane & 31)) : n0 + (lane & 31);
;     float tv[32];
; #pragma unroll
;     for (int i = 0; i < 32; ++i) { const int kk = 2 * i + (lane >> 5); tv[i] = (src >= 0) ? __builtin_nontemporal_load(W + (size_t)(k0 + kk) * N + src) : 0.f; }
; __global__ void __launch_bounds__(NWAVES * 64, 2) fwd_kernel(Args args) {
;     ...
;             for (int it = gw; it < I_O + I_1 + I_2; it += NGW) {
;                 int r = it;
;                 if (r < I_O) { transpose_item<0>(args.in[12], 1024, 1024, (bf16_t*)(ws + WS_WOUT), args.in[11], scr, r, 32, lane); continue; } r -= I_O;
;                 if (r < I_1) { transpose_item<0>(args.in[14], 1024, 4096, (bf16_t*)(ws + WS_WFF1), args.in[13], scr, r, 128, lane); continue; } r -= I_1;
;                 transpose_item<0>(args.in[15], 4096, 1024, (bf16_t*)(ws + WS_WFF2), nullptr, scr, r, 32, lane);
.LBB0_480:
	v_cmp_lt_i32_e32 vcc, s17, v46
	s_and_saveexec_b64 s[10:11], vcc
	s_xor_b64 s[10:11], exec, s[10:11]
	s_cbranch_execz .LBB0_488
	v_cmp_lt_u32_e32 vcc, s18, v46
	s_and_saveexec_b64 s[12:13], vcc
	s_xor_b64 s[12:13], exec, s[12:13]
	s_cbranch_execz .LBB0_483
	v_and_b32_e32 v27, 0x3e0, v55
	v_and_b32_e32 v26, 0x1ffc0, v56
	v_or_b32_e32 v0, v27, v47
	v_readlane_b32 s36, v254, 8
	v_or_b32_e32 v10, v26, v48
	v_lshlrev_b32_e32 v0, 2, v0
	v_readlane_b32 s50, v254, 22
	v_readlane_b32 s51, v254, 23
	v_readlane_b32 s37, v254, 9
	v_readlane_b32 s38, v254, 10
	v_lshl_add_u64 v[8:9], s[50:51], 0, v[0:1]
	v_lshlrev_b32_e32 v0, 12, v10
	v_lshl_add_u64 v[8:9], v[8:9], 0, v[0:1]
	v_add_co_u32_e32 v10, vcc, 0x2000, v8
	v_readlane_b32 s39, v254, 11
	s_nop 0
	v_addc_co_u32_e32 v11, vcc, 0, v9, vcc
	v_add_co_u32_e32 v12, vcc, 0x4000, v8
	v_readlane_b32 s40, v254, 12
	s_nop 0
	v_addc_co_u32_e32 v13, vcc, 0, v9, vcc
	v_add_co_u32_e32 v14, vcc, 0x6000, v8
	v_readlane_b32 s41, v254, 13
	s_nop 0
	v_addc_co_u32_e32 v15, vcc, 0, v9, vcc
	v_add_co_u32_e32 v16, vcc, 0x8000, v8
	v_readlane_b32 s42, v254, 14
	s_nop 0
	v_addc_co_u32_e32 v17, vcc, 0, v9, vcc
	v_add_co_u32_e32 v18, vcc, 0xa000, v8
	v_readlane_b32 s43, v254, 15
	s_nop 0
	v_addc_co_u32_e32 v19, vcc, 0, v9, vcc
	v_add_co_u32_e32 v20, vcc, 0xc000, v8
	v_readlane_b32 s44, v254, 16
	s_nop 0
	v_addc_co_u32_e32 v21, vcc, 0, v9, vcc
	v_add_co_u32_e32 v22, vcc, 0xe000, v8
	v_readlane_b32 s45, v254, 17
	s_nop 0
	v_addc_co_u32_e32 v23, vcc, 0, v9, vcc
	global_load_dword v0, v[8:9], off nt
	global_load_dword v28, v[10:11], off nt
	global_load_dword v29, v[12:13], off nt
	global_load_dword v30, v[14:15], off nt
	global_load_dword v31, v[16:17], off nt
	global_load_dword v32, v[18:19], off nt
	global_load_dword v33, v[20:21], off nt
	global_load_dword v34, v[22:23], off nt
	v_add_co_u32_e32 v10, vcc, 0x10000, v8
	v_readlane_b32 s46, v254, 18
	s_nop 0
	v_addc_co_u32_e32 v11, vcc, 0, v9, vcc
	v_add_co_u32_e32 v12, vcc, 0x12000, v8
	v_readlane_b32 s47, v254, 19
	s_nop 0
	v_addc_co_u32_e32 v13, vcc, 0, v9, vcc
	v_add_co_u32_e32 v14, vcc, 0x14000, v8
	v_readlane_b32 s48, v254, 20
	s_nop 0
	v_addc_co_u32_e32 v15, vcc, 0, v9, vcc
	v_add_co_u32_e32 v16, vcc, 0x16000, v8
	v_readlane_b32 s49, v254, 21
	s_nop 0
	v_addc_co_u32_e32 v17, vcc, 0, v9, vcc
	v_add_co_u32_e32 v18, vcc, 0x18000, v8
	s_nop 1
	v_addc_co_u32_e32 v19, vcc, 0, v9, vcc
	v_add_co_u32_e32 v20, vcc, 0x1a000, v8
	s_nop 1
	v_addc_co_u32_e32 v21, vcc, 0, v9, vcc
	v_add_co_u32_e32 v22, vcc, 0x1c000, v8
	s_nop 1
	v_addc_co_u32_e32 v23, vcc, 0, v9, vcc
	v_add_co_u32_e32 v24, vcc, 0x1e000, v8
	s_nop 1
	v_addc_co_u32_e32 v25, vcc, 0, v9, vcc
	global_load_dword v35, v[10:11], off nt
	global_load_dword v36, v[12:13], off nt
	global_load_dword v37, v[14:15], off nt
	global_load_dword v38, v[16:17], off nt
	global_load_dword v39, v[18:19], off nt
	global_load_dword v40, v[20:21], off nt
	global_load_dword v41, v[22:23], off nt
	global_load_dword v42, v[24:25], off nt
	v_add_co_u32_e32 v10, vcc, 0x20000, v8
	s_nop 1
	v_addc_co_u32_e32 v11, vcc, 0, v9, vcc
	v_add_co_u32_e32 v12, vcc, 0x22000, v8
	s_nop 1
	v_addc_co_u32_e32 v13, vcc, 0, v9, vcc
	v_add_co_u32_e32 v14, vcc, 0x24000, v8
	s_nop 1
	v_addc_co_u32_e32 v15, vcc, 0, v9, vcc
	v_add_co_u32_e32 v16, vcc, 0x26000, v8
	s_nop 1
	v_addc_co_u32_e32 v17, vcc, 0, v9, vcc
	v_add_co_u32_e32 v18, vcc, 0x28000, v8
	s_nop 1
	v_addc_co_u32_e32 v19, vcc, 0, v9, vcc
	v_add_co_u32_e32 v20, vcc, 0x2a000, v8
	s_nop 1
	v_addc_co_u32_e32 v21, vcc, 0, v9, vcc
	v_add_co_u32_e32 v22, vcc, 0x2c000, v8
	s_nop 1
	v_addc_co_u32_e32 v23, vcc, 0, v9, vcc
	v_add_co_u32_e32 v24, vcc, 0x2e000, v8
	s_nop 1
	v_addc_co_u32_e32 v25, vcc, 0, v9, vcc
	global_load_dword v43, v[10:11], off nt
	global_load_dword v44, v[12:13], off nt
	global_load_dword v45, v[14:15], off nt
	global_load_dword v64, v[16:17], off nt
	global_load_dword v65, v[18:19], off nt
	global_load_dword v66, v[20:21], off nt
	global_load_dword v67, v[22:23], off nt
	global_load_dword v68, v[24:25], off nt
	v_add_co_u32_e32 v10, vcc, 0x30000, v8
	s_nop 1
	v_addc_co_u32_e32 v11, vcc, 0, v9, vcc
	v_add_co_u32_e32 v12, vcc, 0x32000, v8
	s_nop 1
	v_addc_co_u32_e32 v13, vcc, 0, v9, vcc
	v_add_co_u32_e32 v14, vcc, 0x34000, v8
	s_nop 1
	v_addc_co_u32_e32 v15, vcc, 0, v9, vcc
	v_add_co_u32_e32 v16, vcc, 0x36000, v8
	s_nop 1
	v_addc_co_u32_e32 v17, vcc, 0, v9, vcc
	v_add_co_u32_e32 v18, vcc, 0x38000, v8
	s_nop 1
	v_addc_co_u32_e32 v19, vcc, 0, v9, vcc
	v_add_co_u32_e32 v20, vcc, 0x3a000, v8
	s_nop 1
	v_addc_co_u32_e32 v21, vcc, 0, v9, vcc
	v_add_co_u32_e32 v22, vcc, 0x3c000, v8
	s_nop 1
	v_addc_co_u32_e32 v23, vcc, 0, v9, vcc
	v_add_co_u32_e32 v8, vcc, 0x3e000, v8
	s_nop 1
	v_addc_co_u32_e32 v9, vcc, 0, v9, vcc
	global_load_dword v10, v[10:11], off nt
	s_nop 0
	global_load_dword v11, v[12:13], off nt
	global_load_dword v24, v[14:15], off nt
	global_load_dword v25, v[16:17], off nt
	global_load_dword v69, v[18:19], off nt
	global_load_dword v70, v[20:21], off nt
	global_load_dword v71, v[22:23], off nt
	global_load_dword v72, v[8:9], off nt
	s_waitcnt vmcnt(0)
; #define LAS __attribute__((address_space(3)))
; __device__ __forceinline__ unsigned pk2(float lo, float hi) { return pg8::cvt_pk_bf16(lo, hi); }
; template <int MAP>
; __device__ __forceinline__ void transpose_item(const float* W, int K, int N, bf16_t* WT, const float* gk, LAS float* scr, int item, int nblk, int lane) {
;     ...
;     for (int i = 0; i < 32; ++i) scr[(2 * i + (lane >> 5)) * 33 + (lane & 31)] = tv[i];
;     asm volatile("s_waitcnt lgkmcnt(0)" ::: "memory");
;     const int c = lane & 7;
; #pragma unroll
;     for (int j = 0; j < 4; ++j) { const int n = (lane >> 3) + 8 * j; const LAS float* s = scr + (8 * c) * 33 + n;
;         u32x4 o; o.x = pk2(s[0 * 33], s[1 * 33]); o.y = pk2(s[2 * 33], s[3 * 33]); o.z = pk2(s[4 * 33], s[5 * 33]); o.w = pk2(s[6 * 33], s[7 * 33]);
;         *(u32x4*)(WT + (size_t)(n0 + n) * K + k0 + 8 * c) = o; }
;     asm volatile("s_waitcnt lgkmcnt(0)" ::: "memory");
	ds_write2_b32 v49, v0, v28 offset1:66
	ds_write2_b32 v49, v29, v30 offset0:132 offset1:198
	ds_write2_b32 v57, v31, v32 offset0:8 offset1:74
	ds_write2_b32 v57, v33, v34 offset0:140 offset1:206
	ds_write2_b32 v58, v35, v36 offset0:16 offset1:82
	ds_write2_b32 v58, v37, v38 offset0:148 offset1:214
	ds_write2_b32 v59, v39, v40 offset0:24 offset1:90
	ds_write2_b32 v59, v41, v42 offset0:156 offset1:222
	ds_write2_b32 v60, v43, v44 offset0:32 offset1:98
	ds_write2_b32 v60, v45, v64 offset0:164 offset1:230
	ds_write2_b32 v61, v65, v66 offset0:40 offset1:106
	ds_write2_b32 v61, v67, v68 offset0:172 offset1:238
	ds_write2_b32 v62, v10, v11 offset0:48 offset1:114
	ds_write2_b32 v62, v24, v25 offset0:180 offset1:246
	ds_write2_b32 v63, v69, v70 offset0:56 offset1:122
	ds_write2_b32 v63, v71, v72 offset0:188 offset1:254
	s_waitcnt lgkmcnt(0)
	ds_read2_b32 v[8:9], v51 offset1:33
	v_lshlrev_b32_e32 v0, 1, v26
	s_waitcnt lgkmcnt(0)
	v_cvt_pk_bf16_f32 v8, v8, v9
	ds_read2_b32 v[10:11], v51 offset0:66 offset1:99
	v_lshl_add_u64 v[14:15], v[2:3], 0, v[0:1]
	v_or_b32_e32 v0, v27, v50
	s_waitcnt lgkmcnt(0)
	v_cvt_pk_bf16_f32 v9, v10, v11
	ds_read2_b32 v[10:11], v51 offset0:132 offset1:165
	v_lshlrev_b32_e32 v0, 13, v0
	s_waitcnt lgkmcnt(0)
	v_cvt_pk_bf16_f32 v10, v10, v11
	ds_read2_b32 v[12:13], v51 offset0:198 offset1:231
	s_waitcnt lgkmcnt(0)
	v_cvt_pk_bf16_f32 v11, v12, v13
	v_lshl_add_u64 v[16:17], v[14:15], 0, v[0:1]
	ds_read2_b32 v[12:13], v51 offset0:8 offset1:41
	global_store_dwordx4 v[16:17], v[8:11], off sc1
	v_or_b32_e32 v0, v27, v52
	v_lshlrev_b32_e32 v0, 13, v0
	s_waitcnt lgkmcnt(0)
	v_cvt_pk_bf16_f32 v8, v12, v13
	ds_read2_b32 v[10:11], v51 offset0:74 offset1:107
	s_waitcnt lgkmcnt(0)
	v_cvt_pk_bf16_f32 v9, v10, v11
	ds_read2_b32 v[10:11], v51 offset0:140 offset1:173
	s_waitcnt lgkmcnt(0)
	v_cvt_pk_bf16_f32 v10, v10, v11
	ds_read2_b32 v[12:13], v51 offset0:206 offset1:239
	s_waitcnt lgkmcnt(0)
	v_cvt_pk_bf16_f32 v11, v12, v13
	v_lshl_add_u64 v[16:17], v[14:15], 0, v[0:1]
	ds_read2_b32 v[12:13], v51 offset0:16 offset1:49
	global_store_dwordx4 v[16:17], v[8:11], off sc1
	v_or_b32_e32 v0, v27, v53
	v_lshlrev_b32_e32 v0, 13, v0
	s_waitcnt lgkmcnt(0)
	v_cvt_pk_bf16_f32 v8, v12, v13
	ds_read2_b32 v[10:11], v51 offset0:82 offset1:115
	s_waitcnt lgkmcnt(0)
	v_cvt_pk_bf16_f32 v9, v10, v11
	ds_read2_b32 v[10:11], v51 offset0:148 offset1:181
	s_waitcnt lgkmcnt(0)
	v_cvt_pk_bf16_f32 v10, v10, v11
	ds_read2_b32 v[12:13], v51 offset0:214 offset1:247
	s_waitcnt lgkmcnt(0)
	v_cvt_pk_bf16_f32 v11, v12, v13
	v_lshl_add_u64 v[16:17], v[14:15], 0, v[0:1]
	ds_read2_b32 v[12:13], v51 offset0:24 offset1:57
	global_store_dwordx4 v[16:17], v[8:11], off sc1
	v_or_b32_e32 v0, v27, v54
	v_lshlrev_b32_e32 v0, 13, v0
	s_waitcnt lgkmcnt(0)
	v_cvt_pk_bf16_f32 v8, v12, v13
	ds_read2_b32 v[10:11], v51 offset0:90 offset1:123
	s_waitcnt lgkmcnt(0)
	v_cvt_pk_bf16_f32 v9, v10, v11
	ds_read2_b32 v[10:11], v51 offset0:156 offset1:189
	s_waitcnt lgkmcnt(0)
	v_cvt_pk_bf16_f32 v10, v10, v11
	ds_read2_b32 v[12:13], v51 offset0:222 offset1:255
	s_waitcnt lgkmcnt(0)
	v_cvt_pk_bf16_f32 v11, v12, v13
	v_lshl_add_u64 v[12:13], v[14:15], 0, v[0:1]
	global_store_dwordx4 v[12:13], v[8:11], off sc1
	s_waitcnt lgkmcnt(0)

; #define LAS __attribute__((address_space(3)))
; __device__ __forceinline__ unsigned pk2(float lo, float hi) { return pg8::cvt_pk_bf16(lo, hi); }
; template <int MAP>
; __device__ __forceinline__ void transpose_item(const float* W, int K, int N, bf16_t* WT, const float* gk, LAS float* scr, int item, int nblk, int lane) {
;     ...
;     for (int i = 0; i < 32; ++i) scr[(2 * i + (lane >> 5)) * 33 + (lane & 31)] = tv[i];
;     asm volatile("s_waitcnt lgkmcnt(0)" ::: "memory");
;     const int c = lane & 7;
; #pragma unroll
;     for (int j = 0; j < 4; ++j) { const int n = (lane >> 3) + 8 * j; const LAS float* s = scr + (8 * c) * 33 + n;
;         u32x4 o; o.x = pk2(s[0 * 33], s[1 * 33]); o.y = pk2(s[2 * 33], s[3 * 33]); o.z = pk2(s[4 * 33], s[5 * 33]); o.w = pk2(s[6 * 33], s[7 * 33]);
;         *(u32x4*)(WT + (size_t)(n0 + n) * K + k0 + 8 * c) = o; }
;     asm volatile("s_waitcnt lgkmcnt(0)" ::: "memory");
.LBB0_486:
	s_waitcnt vmcnt(0)
	ds_write2_b32 v49, v8, v9 offset1:66
	ds_write2_b32 v49, v10, v11 offset0:132 offset1:198
	ds_write2_b32 v57, v12, v13 offset0:8 offset1:74
	ds_write2_b32 v57, v14, v15 offset0:140 offset1:206
	ds_write2_b32 v58, v16, v17 offset0:16 offset1:82
	ds_write2_b32 v58, v18, v19 offset0:148 offset1:214
	ds_write2_b32 v59, v20, v21 offset0:24 offset1:90
	ds_write2_b32 v59, v22, v23 offset0:156 offset1:222
	ds_write2_b32 v60, v24, v25 offset0:32 offset1:98
	ds_write2_b32 v60, v26, v27 offset0:164 offset1:230
	ds_write2_b32 v61, v28, v29 offset0:40 offset1:106
	ds_write2_b32 v61, v30, v31 offset0:172 offset1:238
	ds_write2_b32 v62, v32, v33 offset0:48 offset1:114
	ds_write2_b32 v62, v34, v35 offset0:180 offset1:246
	ds_write2_b32 v63, v38, v39 offset0:56 offset1:122
	ds_write2_b32 v63, v36, v37 offset0:188 offset1:254
	s_waitcnt lgkmcnt(0)
	ds_read2_b32 v[8:9], v51 offset1:33
	v_lshlrev_b32_e32 v0, 1, v41
	s_waitcnt lgkmcnt(0)
	v_cvt_pk_bf16_f32 v8, v8, v9
	ds_read2_b32 v[10:11], v51 offset0:66 offset1:99
	v_lshl_add_u64 v[14:15], v[4:5], 0, v[0:1]
	v_or_b32_e32 v0, v40, v50
	s_waitcnt lgkmcnt(0)
	v_cvt_pk_bf16_f32 v9, v10, v11
	ds_read2_b32 v[10:11], v51 offset0:132 offset1:165
	v_lshlrev_b32_e32 v0, 11, v0
	s_waitcnt lgkmcnt(0)
	v_cvt_pk_bf16_f32 v10, v10, v11
	ds_read2_b32 v[12:13], v51 offset0:198 offset1:231
	s_waitcnt lgkmcnt(0)
	v_cvt_pk_bf16_f32 v11, v12, v13
	v_lshl_add_u64 v[16:17], v[14:15], 0, v[0:1]
	ds_read2_b32 v[12:13], v51 offset0:8 offset1:41
	global_store_dwordx4 v[16:17], v[8:11], off sc1
	v_or_b32_e32 v0, v40, v52
	v_lshlrev_b32_e32 v0, 11, v0
	s_waitcnt lgkmcnt(0)
	v_cvt_pk_bf16_f32 v8, v12, v13
	ds_read2_b32 v[10:11], v51 offset0:74 offset1:107
	s_waitcnt lgkmcnt(0)
	v_cvt_pk_bf16_f32 v9, v10, v11
	ds_read2_b32 v[10:11], v51 offset0:140 offset1:173
	s_waitcnt lgkmcnt(0)
	v_cvt_pk_bf16_f32 v10, v10, v11
	ds_read2_b32 v[12:13], v51 offset0:206 offset1:239
	s_waitcnt lgkmcnt(0)
	v_cvt_pk_bf16_f32 v11, v12, v13
	v_lshl_add_u64 v[16:17], v[14:15], 0, v[0:1]
	ds_read2_b32 v[12:13], v51 offset0:16 offset1:49
	global_store_dwordx4 v[16:17], v[8:11], off sc1
	v_or_b32_e32 v0, v40, v53
	v_lshlrev_b32_e32 v0, 11, v0
	s_waitcnt lgkmcnt(0)
	v_cvt_pk_bf16_f32 v8, v12, v13
	ds_read2_b32 v[10:11], v51 offset0:82 offset1:115
	s_waitcnt lgkmcnt(0)
	v_cvt_pk_bf16_f32 v9, v10, v11
	ds_read2_b32 v[10:11], v51 offset0:148 offset1:181
	s_waitcnt lgkmcnt(0)
	v_cvt_pk_bf16_f32 v10, v10, v11
	ds_read2_b32 v[12:13], v51 offset0:214 offset1:247
	s_waitcnt lgkmcnt(0)
	v_cvt_pk_bf16_f32 v11, v12, v13
	v_lshl_add_u64 v[16:17], v[14:15], 0, v[0:1]
	ds_read2_b32 v[12:13], v51 offset0:24 offset1:57
	global_store_dwordx4 v[16:17], v[8:11], off sc1
	v_or_b32_e32 v0, v40, v54
	v_lshlrev_b32_e32 v0, 11, v0
	s_waitcnt lgkmcnt(0)
	v_cvt_pk_bf16_f32 v8, v12, v13
	ds_read2_b32 v[10:11], v51 offset0:90 offset1:123
	s_waitcnt lgkmcnt(0)
	v_cvt_pk_bf16_f32 v9, v10, v11
	ds_read2_b32 v[10:11], v51 offset0:156 offset1:189
	s_waitcnt lgkmcnt(0)
	v_cvt_pk_bf16_f32 v10, v10, v11
	ds_read2_b32 v[12:13], v51 offset0:222 offset1:255
	s_waitcnt lgkmcnt(0)
	v_cvt_pk_bf16_f32 v11, v12, v13
	v_lshl_add_u64 v[12:13], v[14:15], 0, v[0:1]
	global_store_dwordx4 v[12:13], v[8:11], off sc1
	s_waitcnt lgkmcnt(0)

; #define LAS __attribute__((address_space(3)))
; __device__ __forceinline__ unsigned xb_ld(unsigned* p) { return __hip_atomic_load(p, __ATOMIC_RELAXED, __HIP_MEMORY_SCOPE_AGENT); }
; __device__ __forceinline__ unsigned xb_add(unsigned* p, unsigned v) { return __hip_atomic_fetch_add(p, v, __ATOMIC_RELAXED, __HIP_MEMORY_SCOPE_AGENT); }
; __device__ __forceinline__ unsigned xb_xcc_id() { return (unsigned)__builtin_amdgcn_s_getreg((3 << 11) | 20) & 0xFu; }
; #define SEAM(k) do { if (IN(k) && IN((k) + 1)) { grid_barrier(barw, (k), bst); } } while (0)
; __device__ __forceinline__ void grid_barrier(unsigned* barw, int k, volatile LAS unsigned* st) {
;     asm volatile("s_waitcnt vmcnt(0)" ::: "memory");
;     __syncthreads();
;     if (threadIdx.x == 0) {
;         __builtin_amdgcn_s_waitcnt(0);
;         const unsigned x = xb_xcc_id();
;         unsigned nloc = st[0], nx = st[1];
;         if (nloc == 0u) {
;             const unsigned G = gridDim.x;
;             for (;;) { unsigned sum = 0u, cnt = 0u, mine = 0u;
; #pragma unroll
;                 for (unsigned j = 0; j < 16; ++j) { const unsigned c = xb_ld(barw + 64 * j); sum += c; cnt += (c > 0u) ? 1u : 0u; mine = (j == x) ? c : mine; }
;                 if (sum == G) { nloc = mine; nx = cnt; break; }
;                 __builtin_amdgcn_s_sleep(1); }
;             st[0] = nloc; st[1] = nx;
;         }
;         unsigned* sb = barw + 1024 + k * 2304;
;         const unsigned old = xb_add(sb + 64 * x, 1u);
;         if (old + 1u == nloc) {
;             __builtin_amdgcn_fence(__ATOMIC_RELEASE, "agent");
;             asm volatile("s_waitcnt vmcnt(0)" ::: "memory");
;             const unsigned og = xb_add(sb + 2048, 1u);
;             if (og + 1u == nx) xb_add(sb + 2112, 1u);
;             else while (xb_ld(sb + 2112) == 0u) __builtin_amdgcn_s_sleep(1);
;             __builtin_amdgcn_fence(__ATOMIC_ACQUIRE, "agent");
;             xb_add(sb + 1024 + 64 * x, 1u);
;             asm volatile("s_waitcnt vmcnt(0)" ::: "memory");
;         } else {
;             while (xb_ld(sb + 1024 + 64 * x) == 0u) __builtin_amdgcn_s_sleep(1);
;             __builtin_amdgcn_fence(__ATOMIC_ACQUIRE, "agent");
;             asm volatile("s_waitcnt vmcnt(0)" ::: "memory");
;         }
;     }
;     __syncthreads();
; __global__ void __launch_bounds__(NWAVES * 64, 2) fwd_kernel(Args args) {
;     ...
;     SEAM(2);
.Lgb5_norel:
	v_readlane_b32 s4, v254, 6
	v_readlane_b32 s5, v254, 7
	s_and_b32 s0, s70, 7
	s_lshl_b32 s0, s0, 8
	s_add_i32 s0, s0, 0x114c0
	s_add_u32 s4, s4, s0
	s_addc_u32 s5, s5, 0
	s_lshr_b32 s6, s88, 3
	v_mov_b32_e32 v0, 0
	v_mov_b32_e32 v1, 1
	s_cmpk_gt_i32 s70, 0x7f
	s_cbranch_scc1 .Lgb5_conv
	global_atomic_add v0, v1, s[4:5]
	s_branch .Lgb5_spin
.Lgb5_conv:
	v_readlane_b32 s8, v254, 6
	v_readlane_b32 s9, v254, 7
	s_add_u32 s8, s8, 0x12c00
	s_addc_u32 s9, s9, 0
	s_nop 1
	global_atomic_add v0, v1, s[8:9]

; #define LAS __attribute__((address_space(3)))
; __device__ __forceinline__ unsigned xb_ld(unsigned* p) { return __hip_atomic_load(p, __ATOMIC_RELAXED, __HIP_MEMORY_SCOPE_AGENT); }
; __device__ __forceinline__ unsigned xb_add(unsigned* p, unsigned v) { return __hip_atomic_fetch_add(p, v, __ATOMIC_RELAXED, __HIP_MEMORY_SCOPE_AGENT); }
; __device__ __forceinline__ unsigned xb_xcc_id() { return (unsigned)__builtin_amdgcn_s_getreg((3 << 11) | 20) & 0xFu; }
; #define SEAM(k) do { if (IN(k) && IN((k) + 1)) { grid_barrier(barw, (k), bst); } } while (0)
; __device__ __forceinline__ void grid_barrier(unsigned* barw, int k, volatile LAS unsigned* st) {
;     asm volatile("s_waitcnt vmcnt(0)" ::: "memory");
;     __syncthreads();
;     if (threadIdx.x == 0) {
;         __builtin_amdgcn_s_waitcnt(0);
;         const unsigned x = xb_xcc_id();
;         unsigned nloc = st[0], nx = st[1];
;         if (nloc == 0u) {
;             const unsigned G = gridDim.x;
;             for (;;) { unsigned sum = 0u, cnt = 0u, mine = 0u;
; #pragma unroll
;                 for (unsigned j = 0; j < 16; ++j) { const unsigned c = xb_ld(barw + 64 * j); sum += c; cnt += (c > 0u) ? 1u : 0u; mine = (j == x) ? c : mine; }
;                 if (sum == G) { nloc = mine; nx = cnt; break; }
;                 __builtin_amdgcn_s_sleep(1); }
;             st[0] = nloc; st[1] = nx;
;         }
;         unsigned* sb = barw + 1024 + k * 2304;
;         const unsigned old = xb_add(sb + 64 * x, 1u);
;         if (old + 1u == nloc) {
;             __builtin_amdgcn_fence(__ATOMIC_RELEASE, "agent");
;             asm volatile("s_waitcnt vmcnt(0)" ::: "memory");
;             const unsigned og = xb_add(sb + 2048, 1u);
;             if (og + 1u == nx) xb_add(sb + 2112, 1u);
;             else while (xb_ld(sb + 2112) == 0u) __builtin_amdgcn_s_sleep(1);
;             __builtin_amdgcn_fence(__ATOMIC_ACQUIRE, "agent");
;             xb_add(sb + 1024 + 64 * x, 1u);
;             asm volatile("s_waitcnt vmcnt(0)" ::: "memory");
;         } else {
;             while (xb_ld(sb + 1024 + 64 * x) == 0u) __builtin_amdgcn_s_sleep(1);
;             __builtin_amdgcn_fence(__ATOMIC_ACQUIRE, "agent");
;             asm volatile("s_waitcnt vmcnt(0)" ::: "memory");
;         }
;     }
;     __syncthreads();
; __global__ void __launch_bounds__(NWAVES * 64, 2) fwd_kernel(Args args) {
;     ...
;     SEAM(3);
.LBB0_680:
	v_readlane_b32 s0, v254, 0
	v_readlane_b32 s1, v254, 1
	s_cmp_gt_i32 s1, 4
	s_cselect_b64 s[72:73], -1, 0
	s_and_b64 s[0:1], s[8:9], s[72:73]
	s_andn2_b64 vcc, exec, s[0:1]
	s_cbranch_vccnz .LBB0_709
	s_waitcnt vmcnt(0)
	s_waitcnt vmcnt(0) lgkmcnt(0)
	s_barrier
	s_mov_b64 s[74:75], exec
	v_readlane_b32 s0, v254, 2
	v_readlane_b32 s1, v254, 3
	s_and_b64 s[0:1], s[74:75], s[0:1]
	s_mov_b64 exec, s[0:1]
	s_cbranch_execz .LBB0_708
	s_add_u32 s4, s78, 0x12f40
	s_addc_u32 s5, s79, 0
	v_mov_b32_e32 v0, 0
	v_mov_b32_e32 v1, 1
	global_atomic_add v0, v1, s[4:5]
	s_cmp_lg_u32 s88, 0x100
	s_cbranch_scc1 .Lgb3_orig
	v_mov_b32_e32 v2, 0x23fc8
	ds_read_b32 v2, v2
	s_and_b32 s0, s70, 7
	s_lshl_b32 s0, s0, 8
	s_add_i32 s0, s0, 0x12400
	s_add_u32 s4, s78, s0
	s_addc_u32 s5, s79, 0
	s_lshr_b32 s6, s88, 3
	v_mov_b32_e32 v0, 0
	v_mov_b32_e32 v1, 1
	s_waitcnt vmcnt(0) lgkmcnt(0)
	v_readfirstlane_b32 s9, v2
	s_cmp_eq_u32 s9, 1
	s_cbranch_scc1 .Lgb3_norel
	buffer_wbl2 sc1
	s_waitcnt vmcnt(0)
.Lgb3_norel:
	global_atomic_add v0, v1, s[4:5]

; #define LAS __attribute__((address_space(3)))
; __device__ __forceinline__ unsigned xb_ld(unsigned* p) { return __hip_atomic_load(p, __ATOMIC_RELAXED, __HIP_MEMORY_SCOPE_AGENT); }
; __device__ __forceinline__ unsigned xb_add(unsigned* p, unsigned v) { return __hip_atomic_fetch_add(p, v, __ATOMIC_RELAXED, __HIP_MEMORY_SCOPE_AGENT); }
; __device__ __forceinline__ unsigned xb_xcc_id() { return (unsigned)__builtin_amdgcn_s_getreg((3 << 11) | 20) & 0xFu; }
; #define SEAM(k) do { if (IN(k) && IN((k) + 1)) { grid_barrier(barw, (k), bst); } } while (0)
; __device__ __forceinline__ void grid_barrier(unsigned* barw, int k, volatile LAS unsigned* st) {
;     asm volatile("s_waitcnt vmcnt(0)" ::: "memory");
;     __syncthreads();
;     if (threadIdx.x == 0) {
;         __builtin_amdgcn_s_waitcnt(0);
;         const unsigned x = xb_xcc_id();
;         unsigned nloc = st[0], nx = st[1];
;         if (nloc == 0u) {
;             const unsigned G = gridDim.x;
;             for (;;) { unsigned sum = 0u, cnt = 0u, mine = 0u;
; #pragma unroll
;                 for (unsigned j = 0; j < 16; ++j) { const unsigned c = xb_ld(barw + 64 * j); sum += c; cnt += (c > 0u) ? 1u : 0u; mine = (j == x) ? c : mine; }
;                 if (sum == G) { nloc = mine; nx = cnt; break; }
;                 __builtin_amdgcn_s_sleep(1); }
;             st[0] = nloc; st[1] = nx;
;         }
;         unsigned* sb = barw + 1024 + k * 2304;
;         const unsigned old = xb_add(sb + 64 * x, 1u);
;         if (old + 1u == nloc) {
;             __builtin_amdgcn_fence(__ATOMIC_RELEASE, "agent");
;             asm volatile("s_waitcnt vmcnt(0)" ::: "memory");
;             const unsigned og = xb_add(sb + 2048, 1u);
;             if (og + 1u == nx) xb_add(sb + 2112, 1u);
;             else while (xb_ld(sb + 2112) == 0u) __builtin_amdgcn_s_sleep(1);
;             __builtin_amdgcn_fence(__ATOMIC_ACQUIRE, "agent");
;             xb_add(sb + 1024 + 64 * x, 1u);
;             asm volatile("s_waitcnt vmcnt(0)" ::: "memory");
;         } else {
;             while (xb_ld(sb + 1024 + 64 * x) == 0u) __builtin_amdgcn_s_sleep(1);
;             __builtin_amdgcn_fence(__ATOMIC_ACQUIRE, "agent");
;             asm volatile("s_waitcnt vmcnt(0)" ::: "memory");
;         }
;     }
;     __syncthreads();
; __global__ void __launch_bounds__(NWAVES * 64, 2) fwd_kernel(Args args) {
;     ...
;     SEAM(4);
.Lgb2_pf:
	global_load_dword v2, v0, s[4:5] sc1
	s_waitcnt vmcnt(0)
	v_readfirstlane_b32 s7, v2
	s_cmp_ge_u32 s7, 128
	s_cbranch_scc1 .Lgb2_pfok
	s_sleep 1
	s_branch .Lgb2_pf
